# v13 plus next-item L2 warm-up loads in the INPROJ0 weight-conversion tail only
# speedup vs baseline: 1.0016x; 1.0008x over previous
.LBB0_327:
	s_add_i32 s73, s57, 0x3a8
	s_cmpk_gt_u32 s73, 0x27f
	s_mov_b64 s[4:5], -1
	s_cbranch_scc0 .LBB0_382
	s_cmpk_gt_u32 s73, 0x297
	s_cbranch_scc0 .LBB0_377
	s_cmpk_gt_u32 s73, 0x2a7
	s_cbranch_scc0 .LBB0_372
	s_cmpk_gt_u32 s73, 0x3a7
	s_cbranch_scc0 .LBB0_336
	s_cmpk_gt_u32 s73, 0x7a7
	s_cbranch_scc0 .LBB0_333
	s_add_i32 s0, s56, 0xffffe620
	v_mov_b32_e32 v21, v164
	s_and_b32 s1, s0, 0x7fffffc0
	s_add_i32 s0, s55, 0xfffe6200
	s_and_b32 s0, s0, 0x3c0
	v_and_b32_e32 v24, 63, v21
	v_bfe_u32 v25, v21, 6, 2
	v_or_b32_e32 v1, s0, v24
	v_or_b32_e32 v0, s1, v25
	v_lshlrev_b32_e32 v16, 2, v1
	v_lshl_add_u64 v[2:3], s[30:31], 0, v[16:17]
	v_or_b32_e32 v16, 4, v0
	v_lshlrev_b64 v[6:7], 12, v[16:17]
	v_or_b32_e32 v16, 8, v0
	v_lshlrev_b64 v[8:9], 12, v[16:17]
	v_or_b32_e32 v16, 12, v0
	v_lshlrev_b64 v[10:11], 12, v[16:17]
	v_or_b32_e32 v16, 16, v0
	v_lshlrev_b64 v[12:13], 12, v[16:17]
	v_or_b32_e32 v16, 20, v0
	v_lshlrev_b64 v[14:15], 12, v[16:17]
	v_or_b32_e32 v16, 24, v0
	v_mov_b32_e32 v1, v17
	v_lshlrev_b64 v[18:19], 12, v[16:17]
	v_or_b32_e32 v16, 28, v0
	v_lshlrev_b64 v[4:5], 12, v[0:1]
	v_lshlrev_b64 v[22:23], 12, v[16:17]
	v_lshl_add_u64 v[4:5], v[2:3], 0, v[4:5]
	v_lshl_add_u64 v[22:23], v[2:3], 0, v[22:23]
	v_or_b32_e32 v16, 32, v0
	v_lshl_add_u64 v[6:7], v[2:3], 0, v[6:7]
	v_lshl_add_u64 v[8:9], v[2:3], 0, v[8:9]
	v_lshl_add_u64 v[10:11], v[2:3], 0, v[10:11]
	v_lshl_add_u64 v[12:13], v[2:3], 0, v[12:13]
	v_lshl_add_u64 v[14:15], v[2:3], 0, v[14:15]
	v_lshl_add_u64 v[18:19], v[2:3], 0, v[18:19]
	global_load_dword v26, v[4:5], off
	global_load_dword v27, v[6:7], off
	global_load_dword v28, v[8:9], off
	global_load_dword v29, v[10:11], off
	global_load_dword v30, v[12:13], off
	global_load_dword v31, v[14:15], off
	global_load_dword v32, v[18:19], off
	s_nop 0
	global_load_dword v22, v[22:23], off
	v_lshlrev_b64 v[4:5], 12, v[16:17]
	v_or_b32_e32 v16, 36, v0
	v_lshlrev_b64 v[6:7], 12, v[16:17]
	v_or_b32_e32 v16, 40, v0
	v_lshlrev_b64 v[8:9], 12, v[16:17]
	v_or_b32_e32 v16, 44, v0
	v_lshlrev_b64 v[10:11], 12, v[16:17]
	v_or_b32_e32 v16, 48, v0
	v_lshlrev_b64 v[12:13], 12, v[16:17]
	v_or_b32_e32 v16, 52, v0
	v_lshlrev_b64 v[14:15], 12, v[16:17]
	v_or_b32_e32 v16, 56, v0
	v_lshlrev_b64 v[18:19], 12, v[16:17]
	v_or_b32_e32 v16, 60, v0
	v_lshlrev_b64 v[0:1], 12, v[16:17]
	v_lshl_add_u64 v[4:5], v[2:3], 0, v[4:5]
	v_lshl_add_u64 v[6:7], v[2:3], 0, v[6:7]
	v_lshl_add_u64 v[8:9], v[2:3], 0, v[8:9]
	v_lshl_add_u64 v[0:1], v[2:3], 0, v[0:1]
	v_lshl_add_u64 v[10:11], v[2:3], 0, v[10:11]
	v_lshl_add_u64 v[12:13], v[2:3], 0, v[12:13]
	v_lshl_add_u64 v[14:15], v[2:3], 0, v[14:15]
	v_lshl_add_u64 v[18:19], v[2:3], 0, v[18:19]
	global_load_dword v2, v[4:5], off
	global_load_dword v3, v[6:7], off
	s_nop 0
	global_load_dword v4, v[8:9], off
	global_load_dword v5, v[10:11], off
	global_load_dword v6, v[12:13], off
	global_load_dword v7, v[14:15], off
	s_nop 0
	global_load_dword v8, v[18:19], off
	s_nop 0
	global_load_dword v0, v[0:1], off
	s_add_i32 s98, s73, 0xb0
	s_cmpk_lt_i32 s98, 0xba8
	s_cselect_b32 s98, s98, s73
	s_cmpk_gt_u32 s98, 0x7a7
	s_cbranch_scc1 .LpfA_ff2
	s_add_i32 s98, s98, 0xfffffc58
	s_lshr_b32 s99, s98, 6
	s_and_b32 s98, s98, 63
	s_lshl_b32 s99, s99, 20
	s_lshl_b32 s98, s98, 8
	s_add_i32 s98, s98, s99
	s_add_u32 s100, s28, s98
	s_addc_u32 s101, s29, 0
	s_mov_b32 s99, 14
	s_branch .LpfA_go
.LpfA_ff2:
	s_add_i32 s98, s98, 0xfffff858
	s_lshr_b32 s99, s98, 4
	s_and_b32 s98, s98, 15
	s_lshl_b32 s99, s99, 18
	s_lshl_b32 s98, s98, 8
	s_add_i32 s98, s98, s99
	s_add_u32 s100, s30, s98
	s_addc_u32 s101, s31, 0
	s_mov_b32 s99, 12
.LpfA_go:
	v_bfe_u32 v222, v164, 6, 2
	v_bfe_u32 v223, v164, 4, 2
	v_lshl_add_u32 v222, v222, 4, v223
	v_lshlrev_b32_e32 v222, s99, v222
	v_and_b32_e32 v223, 15, v164
	v_lshl_add_u32 v222, v223, 4, v222
	s_lshl_b32 s98, 4, s99
	global_load_dwordx4 v[224:227], v222, s[100:101]
	s_add_u32 s100, s100, s98
	s_addc_u32 s101, s101, 0
	global_load_dwordx4 v[228:231], v222, s[100:101]
	s_add_u32 s100, s100, s98
	s_addc_u32 s101, s101, 0
	global_load_dwordx4 v[232:235], v222, s[100:101]
	s_add_u32 s100, s100, s98
	s_addc_u32 s101, s101, 0
	global_load_dwordx4 v[236:239], v222, s[100:101]
	v_lshlrev_b32_e32 v1, 3, v21
	v_mul_u32_u24_e32 v9, 0x104, v25
	v_lshlrev_b32_e32 v10, 2, v24
	v_and_b32_e32 v1, 56, v1
	v_add3_u32 v9, s23, v9, v10
	v_bfe_u32 v21, v21, 3, 5
	v_lshlrev_b32_e32 v16, 1, v1
	s_lshl_b32 s1, s1, 1
	s_add_u32 s4, s45, s1
	s_addc_u32 s5, s46, 0
	v_lshl_add_u64 v[24:25], s[4:5], 0, v[16:17]
	s_mov_b64 s[4:5], 0
	s_waitcnt vmcnt(19)
	ds_write_b32 v9, v26
	s_waitcnt vmcnt(18)
	ds_write_b32 v9, v27 offset:1040
	s_waitcnt vmcnt(17)
	ds_write_b32 v9, v28 offset:2080
	s_waitcnt vmcnt(16)
	ds_write_b32 v9, v29 offset:3120
	s_waitcnt vmcnt(15)
	ds_write_b32 v9, v30 offset:4160
	s_waitcnt vmcnt(14)
	ds_write_b32 v9, v31 offset:5200
	s_waitcnt vmcnt(13)
	ds_write_b32 v9, v32 offset:6240
	s_waitcnt vmcnt(12)
	ds_write_b32 v9, v22 offset:7280
	s_waitcnt vmcnt(11)
	ds_write_b32 v9, v2 offset:8320
	s_waitcnt vmcnt(10)
	ds_write_b32 v9, v3 offset:9360
	s_waitcnt vmcnt(9)
	ds_write_b32 v9, v4 offset:10400
	s_waitcnt vmcnt(8)
	ds_write_b32 v9, v5 offset:11440
	s_waitcnt vmcnt(7)
	ds_write_b32 v9, v6 offset:12480
	s_waitcnt vmcnt(6)
	ds_write_b32 v9, v7 offset:13520
	s_waitcnt vmcnt(5)
	ds_write_b32 v9, v8 offset:14560
	s_waitcnt vmcnt(4)
	ds_write_b32 v9, v0 offset:15600
	v_mul_u32_u24_e32 v0, 0x41, v1
	v_lshlrev_b32_e32 v0, 2, v0
	v_lshlrev_b32_e32 v1, 2, v21
	v_add3_u32 v2, s23, v0, v1
	s_waitcnt lgkmcnt(0)
	s_barrier
	ds_read2_b32 v[4:5], v2 offset1:32
	v_add3_u32 v0, s23, v1, v0
	ds_read2_b32 v[6:7], v0 offset0:65 offset1:97
	ds_read2_b32 v[8:9], v2 offset0:130 offset1:162
	ds_read2_b32 v[10:11], v2 offset0:195 offset1:227
	v_add_u32_e32 v0, 0x400, v2
	ds_read2_b32 v[12:13], v0 offset0:4 offset1:36
	ds_read2_b32 v[14:15], v0 offset0:69 offset1:101
	ds_read2_b32 v[18:19], v0 offset0:134 offset1:166
	ds_read2_b32 v[22:23], v0 offset0:199 offset1:231
	s_waitcnt lgkmcnt(6)
	v_cvt_pk_bf16_f32 v0, v4, v6
	v_or_b32_e32 v4, s0, v21
	v_lshlrev_b32_e32 v16, 13, v4
	s_waitcnt lgkmcnt(4)
	v_cvt_pk_bf16_f32 v1, v8, v10
	s_waitcnt lgkmcnt(2)
	v_cvt_pk_bf16_f32 v2, v12, v14
	s_waitcnt lgkmcnt(0)
	v_cvt_pk_bf16_f32 v3, v18, v22
	v_lshl_add_u64 v[26:27], v[24:25], 0, v[16:17]
	v_or_b32_e32 v16, 0x40000, v16
	global_store_dwordx4 v[26:27], v[0:3], off
	s_nop 1
	v_cvt_pk_bf16_f32 v0, v5, v7
	v_cvt_pk_bf16_f32 v1, v9, v11
	v_cvt_pk_bf16_f32 v2, v13, v15
	v_cvt_pk_bf16_f32 v3, v19, v23
	v_lshl_add_u64 v[4:5], v[24:25], 0, v[16:17]
	global_store_dwordx4 v[4:5], v[0:3], off
	s_barrier
.LBB0_333:
	s_andn2_b64 vcc, exec, s[4:5]
	s_cbranch_vccnz .LBB0_335
	v_mov_b32_e32 v21, v164
	s_add_i32 s0, s55, 0xffff6200
	s_and_b32 s0, s0, 0xfc0
	v_and_b32_e32 v24, 63, v21
	s_and_b32 s36, s57, 0xffffffc0
	v_bfe_u32 v25, v21, 6, 2
	v_or_b32_e32 v1, s0, v24
	v_or_b32_e32 v0, s36, v25
	v_lshlrev_b32_e32 v16, 2, v1
	v_lshl_add_u64 v[2:3], s[28:29], 0, v[16:17]
	v_or_b32_e32 v16, 4, v0
	v_lshlrev_b64 v[6:7], 14, v[16:17]
	v_or_b32_e32 v16, 8, v0
	v_lshlrev_b64 v[8:9], 14, v[16:17]
	v_or_b32_e32 v16, 12, v0
	v_lshlrev_b64 v[10:11], 14, v[16:17]
	v_or_b32_e32 v16, 16, v0
	v_lshlrev_b64 v[12:13], 14, v[16:17]
	v_or_b32_e32 v16, 20, v0
	v_lshlrev_b64 v[14:15], 14, v[16:17]
	v_or_b32_e32 v16, 24, v0
	v_mov_b32_e32 v1, v17
	v_lshlrev_b64 v[18:19], 14, v[16:17]
	v_or_b32_e32 v16, 28, v0
	v_lshlrev_b64 v[4:5], 14, v[0:1]
	v_lshlrev_b64 v[22:23], 14, v[16:17]
	v_lshl_add_u64 v[4:5], v[2:3], 0, v[4:5]
	v_lshl_add_u64 v[22:23], v[2:3], 0, v[22:23]
	v_or_b32_e32 v16, 32, v0
	v_lshl_add_u64 v[6:7], v[2:3], 0, v[6:7]
	v_lshl_add_u64 v[8:9], v[2:3], 0, v[8:9]
	v_lshl_add_u64 v[10:11], v[2:3], 0, v[10:11]
	v_lshl_add_u64 v[12:13], v[2:3], 0, v[12:13]
	v_lshl_add_u64 v[14:15], v[2:3], 0, v[14:15]
	v_lshl_add_u64 v[18:19], v[2:3], 0, v[18:19]
	global_load_dword v26, v[4:5], off
	global_load_dword v27, v[6:7], off
	global_load_dword v28, v[8:9], off
	global_load_dword v29, v[10:11], off
	global_load_dword v30, v[12:13], off
	global_load_dword v31, v[14:15], off
	global_load_dword v32, v[18:19], off
	s_nop 0
	global_load_dword v22, v[22:23], off
	v_lshlrev_b64 v[4:5], 14, v[16:17]
	v_or_b32_e32 v16, 36, v0
	v_lshlrev_b64 v[6:7], 14, v[16:17]
	v_or_b32_e32 v16, 40, v0
	v_lshlrev_b64 v[8:9], 14, v[16:17]
	v_or_b32_e32 v16, 44, v0
	v_lshlrev_b64 v[10:11], 14, v[16:17]
	v_or_b32_e32 v16, 48, v0
	v_lshlrev_b64 v[12:13], 14, v[16:17]
	v_or_b32_e32 v16, 52, v0
	v_lshlrev_b64 v[14:15], 14, v[16:17]
	v_or_b32_e32 v16, 56, v0
	v_lshlrev_b64 v[18:19], 14, v[16:17]
	v_or_b32_e32 v16, 60, v0
	v_lshlrev_b64 v[0:1], 14, v[16:17]
	v_lshl_add_u64 v[4:5], v[2:3], 0, v[4:5]
	v_lshl_add_u64 v[6:7], v[2:3], 0, v[6:7]
	v_lshl_add_u64 v[8:9], v[2:3], 0, v[8:9]
	v_lshl_add_u64 v[0:1], v[2:3], 0, v[0:1]
	v_lshl_add_u64 v[10:11], v[2:3], 0, v[10:11]
	v_lshl_add_u64 v[12:13], v[2:3], 0, v[12:13]
	v_lshl_add_u64 v[14:15], v[2:3], 0, v[14:15]
	v_lshl_add_u64 v[18:19], v[2:3], 0, v[18:19]
	global_load_dword v2, v[4:5], off
	global_load_dword v3, v[6:7], off
	s_nop 0
	global_load_dword v4, v[8:9], off
	global_load_dword v5, v[10:11], off
	global_load_dword v6, v[12:13], off
	global_load_dword v7, v[14:15], off
	s_nop 0
	global_load_dword v8, v[18:19], off
	s_nop 0
	global_load_dword v0, v[0:1], off
	s_add_i32 s98, s73, 0xb0
	s_cmpk_lt_i32 s98, 0xba8
	s_cselect_b32 s98, s98, s73
	s_cmpk_gt_u32 s98, 0x7a7
	s_cbranch_scc1 .LpfB_ff2
	s_add_i32 s98, s98, 0xfffffc58
	s_lshr_b32 s99, s98, 6
	s_and_b32 s98, s98, 63
	s_lshl_b32 s99, s99, 20
	s_lshl_b32 s98, s98, 8
	s_add_i32 s98, s98, s99
	s_add_u32 s100, s28, s98
	s_addc_u32 s101, s29, 0
	s_mov_b32 s99, 14
	s_branch .LpfB_go

.LpfB_go:
	v_bfe_u32 v222, v164, 6, 2
	v_bfe_u32 v223, v164, 4, 2
	v_lshl_add_u32 v222, v222, 4, v223
	v_lshlrev_b32_e32 v222, s99, v222
	v_and_b32_e32 v223, 15, v164
	v_lshl_add_u32 v222, v223, 4, v222
	s_lshl_b32 s98, 4, s99
	global_load_dwordx4 v[224:227], v222, s[100:101]
	s_add_u32 s100, s100, s98
	s_addc_u32 s101, s101, 0
	global_load_dwordx4 v[228:231], v222, s[100:101]
	s_add_u32 s100, s100, s98
	s_addc_u32 s101, s101, 0
	global_load_dwordx4 v[232:235], v222, s[100:101]
	s_add_u32 s100, s100, s98
	s_addc_u32 s101, s101, 0
	global_load_dwordx4 v[236:239], v222, s[100:101]
	v_lshlrev_b32_e32 v1, 3, v21
	v_mul_u32_u24_e32 v9, 0x104, v25
	v_lshlrev_b32_e32 v10, 2, v24
	v_and_b32_e32 v1, 56, v1
	v_add3_u32 v9, s23, v9, v10
	v_bfe_u32 v21, v21, 3, 5
	v_lshlrev_b32_e32 v16, 1, v1
	s_lshl_b64 s[4:5], s[36:37], 1
	s_add_u32 s4, s47, s4
	s_addc_u32 s5, s48, s5
	v_lshl_add_u64 v[24:25], s[4:5], 0, v[16:17]
	s_waitcnt vmcnt(19)
	ds_write_b32 v9, v26
	s_waitcnt vmcnt(18)
	ds_write_b32 v9, v27 offset:1040
	s_waitcnt vmcnt(17)
	ds_write_b32 v9, v28 offset:2080
	s_waitcnt vmcnt(16)
	ds_write_b32 v9, v29 offset:3120
	s_waitcnt vmcnt(15)
	ds_write_b32 v9, v30 offset:4160
	s_waitcnt vmcnt(14)
	ds_write_b32 v9, v31 offset:5200
	s_waitcnt vmcnt(13)
	ds_write_b32 v9, v32 offset:6240
	s_waitcnt vmcnt(12)
	ds_write_b32 v9, v22 offset:7280
	s_waitcnt vmcnt(11)
	ds_write_b32 v9, v2 offset:8320
	s_waitcnt vmcnt(10)
	ds_write_b32 v9, v3 offset:9360
	s_waitcnt vmcnt(9)
	ds_write_b32 v9, v4 offset:10400
	s_waitcnt vmcnt(8)
	ds_write_b32 v9, v5 offset:11440
	s_waitcnt vmcnt(7)
	ds_write_b32 v9, v6 offset:12480
	s_waitcnt vmcnt(6)
	ds_write_b32 v9, v7 offset:13520
	s_waitcnt vmcnt(5)
	ds_write_b32 v9, v8 offset:14560
	s_waitcnt vmcnt(4)
	ds_write_b32 v9, v0 offset:15600
	v_mul_u32_u24_e32 v0, 0x41, v1
	v_lshlrev_b32_e32 v0, 2, v0
	v_lshlrev_b32_e32 v1, 2, v21
	v_add3_u32 v2, s23, v0, v1
	s_waitcnt lgkmcnt(0)
	s_barrier
	ds_read2_b32 v[4:5], v2 offset1:32
	v_add3_u32 v0, s23, v1, v0
	ds_read2_b32 v[6:7], v0 offset0:65 offset1:97
	ds_read2_b32 v[8:9], v2 offset0:130 offset1:162
	ds_read2_b32 v[10:11], v2 offset0:195 offset1:227
	v_add_u32_e32 v0, 0x400, v2
	ds_read2_b32 v[12:13], v0 offset0:4 offset1:36
	ds_read2_b32 v[14:15], v0 offset0:69 offset1:101
	ds_read2_b32 v[18:19], v0 offset0:134 offset1:166
	ds_read2_b32 v[22:23], v0 offset0:199 offset1:231
	s_waitcnt lgkmcnt(6)
	v_cvt_pk_bf16_f32 v0, v4, v6
	v_or_b32_e32 v4, s0, v21
	v_lshlrev_b32_e32 v16, 11, v4
	s_waitcnt lgkmcnt(4)
	v_cvt_pk_bf16_f32 v1, v8, v10
	s_waitcnt lgkmcnt(2)
	v_cvt_pk_bf16_f32 v2, v12, v14
	s_waitcnt lgkmcnt(0)
	v_cvt_pk_bf16_f32 v3, v18, v22
	v_lshl_add_u64 v[26:27], v[24:25], 0, v[16:17]
	v_or_b32_e32 v16, 0x10000, v16
	global_store_dwordx4 v[26:27], v[0:3], off
	s_nop 1
	v_cvt_pk_bf16_f32 v0, v5, v7
	v_cvt_pk_bf16_f32 v1, v9, v11
	v_cvt_pk_bf16_f32 v2, v13, v15
	v_cvt_pk_bf16_f32 v3, v19, v23
	v_lshl_add_u64 v[4:5], v[24:25], 0, v[16:17]
	global_store_dwordx4 v[4:5], v[0:3], off
	s_barrier
